# LN1/LN2 split-K pre-pass stops at the last real row; P3's sixth conversion block goes to the workgroups without real tail rows; P9 reduce on real rows; back-edge rotation
# speedup vs baseline: 1.0145x; 1.0145x over previous
.LBB0_452:
	s_add_i32 s11, s7, s20
	s_add_i32 s21, s11, 0x2000
	s_cmpk_gt_i32 s21, 0x213f
	s_cselect_b64 s[70:71], -1, 0
	s_and_b64 vcc, exec, s[70:71]
	s_cbranch_vccnz .LBB0_466
	s_cmpk_gt_i32 s21, 0x203f
	s_mov_b64 s[74:75], -1
	s_cbranch_scc0 .LBB0_455
	s_sub_i32 s0, s11, 64
	v_readlane_b32 s52, v255, 7
	s_lshl_b64 s[22:23], s[0:1], 14
	v_readlane_b32 s54, v255, 9
	v_readlane_b32 s55, v255, 10
	s_add_u32 s0, s54, s22
	s_addc_u32 s22, s55, s23
	s_cmpk_lt_u32 s21, 0x2140
	v_readlane_b32 s53, v255, 8
	v_readlane_b32 s56, v255, 11
	v_readlane_b32 s57, v255, 12
	v_readlane_b32 s58, v255, 13
	v_readlane_b32 s59, v255, 14
	v_readlane_b32 s60, v255, 15
	v_readlane_b32 s61, v255, 16
	v_readlane_b32 s62, v255, 17
	v_readlane_b32 s63, v255, 18
	v_readlane_b32 s64, v255, 19
	v_readlane_b32 s65, v255, 20
	v_readlane_b32 s66, v255, 21
	v_readlane_b32 s67, v255, 22
	s_cselect_b32 s79, s22, 0
	s_cselect_b32 s78, s0, 0
	s_mov_b64 s[74:75], 0

.LBB0_484:
	v_mbcnt_lo_u32_b32 v135, -1, 0
	v_mbcnt_hi_u32_b32 v135, -1, v135
	v_lshrrev_b32_e32 v136, 2, v135
	v_and_b32_e32 v137, 3, v135
	v_lshlrev_b32_e32 v230, 4, v137
	v_lshlrev_b32_e32 v231, 15, v137
	v_lshl_add_u32 v231, v136, 3, v231
	v_readlane_b32 s7, v254, 17
	v_readlane_b32 s1, v254, 16
	v_readlane_b32 s13, v254, 15
	s_mov_b32 s11, 0x42fe0000
	s_mov_b32 s5, 0
	v_lshlrev_b32_e32 v139, 11, v137
	v_lshl_add_u32 v139, v136, 2, v139
	s_nop 1
	v_add_u32_e32 v139, s7, v139
	v_lshlrev_b32_e32 v174, 2, v135
	v_xor_b32_e32 v192, 0x10, v174
	v_xor_b32_e32 v193, 0x20, v174
	v_xor_b32_e32 v194, 0x40, v174
	v_xor_b32_e32 v195, 0x80, v174
	v_lshrrev_b32_e32 v175, 5, v135
	v_and_b32_e32 v176, 31, v135
	v_lshlrev_b32_e32 v212, 9, v175
	v_lshl_add_u32 v212, v176, 4, v212
	v_add_u32_e32 v212, s7, v212
	v_lshlrev_b32_e32 v213, 12, v175
	v_lshl_add_u32 v213, v176, 4, v213
	v_readlane_b32 s52, v255, 61
	v_readlane_b32 s53, v255, 62
	v_mul_u32_u24_e32 v138, 0x56000, v136
	v_lshl_add_u32 v138, v137, 4, v138
	s_mul_i32 s3, s1, 0x2b00000
	s_nop 1
	s_add_u32 s52, s52, s3
	s_addc_u32 s53, s53, 0
	s_mov_b32 s0, s13
	s_cmpk_lg_i32 s33, 0x100
	s_cbranch_scc1 .Lc16p3_ffn2_start
	s_sub_i32 s0, s13, 0xa0
	s_cmp_lt_i32 s0, 0
	s_cselect_b32 s3, 0x100, 0
	s_add_i32 s0, s0, s3
	s_nop 0
.Lc16p3_ffn2_start:
	s_cmp_ge_u32 s0, 0x560
	s_cbranch_scc1 .Lc16p3_ffn2_done
	s_lshl_b32 s3, s0, 6
	s_add_u32 s54, s52, s3
	s_addc_u32 s55, s53, 0
	global_load_dwordx4 v[6:9], v138, s[54:55]
	s_add_u32 s54, s54, 0x15800
	s_addc_u32 s55, s55, 0
	global_load_dwordx4 v[10:13], v138, s[54:55]
	s_add_u32 s54, s54, 0x15800
	s_addc_u32 s55, s55, 0
	global_load_dwordx4 v[14:17], v138, s[54:55]
	s_add_u32 s54, s54, 0x15800
	s_addc_u32 s55, s55, 0
	global_load_dwordx4 v[18:21], v138, s[54:55]
	s_add_u32 s54, s54, 0x51f800
	s_addc_u32 s55, s55, 0
	global_load_dwordx4 v[22:25], v138, s[54:55]
	s_add_u32 s54, s54, 0x15800
	s_addc_u32 s55, s55, 0
	global_load_dwordx4 v[26:29], v138, s[54:55]
	s_add_u32 s54, s54, 0x15800
	s_addc_u32 s55, s55, 0
	global_load_dwordx4 v[30:33], v138, s[54:55]
	s_add_u32 s54, s54, 0x15800
	s_addc_u32 s55, s55, 0
	global_load_dwordx4 v[34:37], v138, s[54:55]
	s_add_u32 s54, s54, 0x51f800
	s_addc_u32 s55, s55, 0
	global_load_dwordx4 v[38:41], v138, s[54:55]
	s_add_u32 s54, s54, 0x15800
	s_addc_u32 s55, s55, 0
	global_load_dwordx4 v[42:45], v138, s[54:55]
	s_add_u32 s54, s54, 0x15800
	s_addc_u32 s55, s55, 0
	global_load_dwordx4 v[46:49], v138, s[54:55]
	s_add_u32 s54, s54, 0x15800
	s_addc_u32 s55, s55, 0
	global_load_dwordx4 v[50:53], v138, s[54:55]
	s_add_u32 s54, s54, 0x51f800
	s_addc_u32 s55, s55, 0
	global_load_dwordx4 v[54:57], v138, s[54:55]
	s_add_u32 s54, s54, 0x15800
	s_addc_u32 s55, s55, 0
	global_load_dwordx4 v[58:61], v138, s[54:55]
	s_add_u32 s54, s54, 0x15800
	s_addc_u32 s55, s55, 0
	global_load_dwordx4 v[62:65], v138, s[54:55]
	s_add_u32 s54, s54, 0x15800
	s_addc_u32 s55, s55, 0
	global_load_dwordx4 v[66:69], v138, s[54:55]
	s_add_u32 s54, s54, 0x51f800
	s_addc_u32 s55, s55, 0
	global_load_dwordx4 v[70:73], v138, s[54:55]
	s_add_u32 s54, s54, 0x15800
	s_addc_u32 s55, s55, 0
	global_load_dwordx4 v[74:77], v138, s[54:55]
	s_add_u32 s54, s54, 0x15800
	s_addc_u32 s55, s55, 0
	global_load_dwordx4 v[78:81], v138, s[54:55]
	s_add_u32 s54, s54, 0x15800
	s_addc_u32 s55, s55, 0
	global_load_dwordx4 v[82:85], v138, s[54:55]
	s_add_u32 s54, s54, 0x51f800
	s_addc_u32 s55, s55, 0
	global_load_dwordx4 v[86:89], v138, s[54:55]
	s_add_u32 s54, s54, 0x15800
	s_addc_u32 s55, s55, 0
	global_load_dwordx4 v[90:93], v138, s[54:55]
	s_add_u32 s54, s54, 0x15800
	s_addc_u32 s55, s55, 0
	global_load_dwordx4 v[94:97], v138, s[54:55]
	s_add_u32 s54, s54, 0x15800
	s_addc_u32 s55, s55, 0
	global_load_dwordx4 v[98:101], v138, s[54:55]
	s_add_u32 s54, s54, 0x51f800
	s_addc_u32 s55, s55, 0
	global_load_dwordx4 v[102:105], v138, s[54:55]
	s_add_u32 s54, s54, 0x15800
	s_addc_u32 s55, s55, 0
	global_load_dwordx4 v[106:109], v138, s[54:55]
	s_add_u32 s54, s54, 0x15800
	s_addc_u32 s55, s55, 0
	global_load_dwordx4 v[110:113], v138, s[54:55]
	s_add_u32 s54, s54, 0x15800
	s_addc_u32 s55, s55, 0
	global_load_dwordx4 v[114:117], v138, s[54:55]
	s_add_u32 s54, s54, 0x51f800
	s_addc_u32 s55, s55, 0
	global_load_dwordx4 v[118:121], v138, s[54:55]
	s_add_u32 s54, s54, 0x15800
	s_addc_u32 s55, s55, 0
	global_load_dwordx4 v[122:125], v138, s[54:55]
	s_add_u32 s54, s54, 0x15800
	s_addc_u32 s55, s55, 0
	global_load_dwordx4 v[126:129], v138, s[54:55]
	s_add_u32 s54, s54, 0x15800
	s_addc_u32 s55, s55, 0
	global_load_dwordx4 v[130:133], v138, s[54:55]

.LBB0_1472:
	s_add_i32 s10, s20, 0x2000
	s_cmpk_gt_i32 s10, 0x213f
	s_cselect_b64 s[10:11], -1, 0
	s_and_b64 vcc, exec, s[10:11]
	s_cbranch_vccnz .LBB0_1471
	s_ashr_i32 s21, s20, 4
	s_and_b32 s22, s12, 0xff00
	s_and_b32 s21, s21, -16
	s_lshl_b32 s22, s22, 2
	v_readlane_b32 s24, v254, 43
	v_readlane_b32 s25, v254, 44
	s_add_u32 s22, s24, s22
	s_waitcnt vmcnt(27)
	v_lshlrev_b32_e32 v18, 2, v222
	s_addc_u32 s23, s25, 0
	v_ashrrev_i32_e32 v19, 31, v18
	s_waitcnt vmcnt(23)
	v_lshl_add_u64 v[34:35], v[18:19], 2, s[22:23]
	s_or_b32 s22, s21, s9
	s_lshl_b32 s22, s22, 3
	s_ashr_i32 s23, s22, 31
	s_lshl_b64 s[22:23], s[22:23], 18
	v_lshl_add_u64 v[30:31], v[34:35], 0, s[22:23]
	v_add_co_u32_e32 v6, vcc, s1, v30
	s_waitcnt vmcnt(22)
	v_lshl_add_u64 v[36:37], v[18:19], 1, s[6:7]
	v_addc_co_u32_e32 v7, vcc, 0, v31, vcc
	v_add_co_u32_e32 v10, vcc, s13, v30
	global_load_dwordx4 v[2:5], v[30:31], off
	s_nop 0
	global_load_dwordx4 v[6:9], v[6:7], off
	v_addc_co_u32_e32 v11, vcc, 0, v31, vcc
	v_add_co_u32_e32 v14, vcc, s14, v30
	s_or_b32 s21, s21, s2
	s_nop 0
	v_addc_co_u32_e32 v15, vcc, 0, v31, vcc
	v_add_co_u32_e32 v20, vcc, s15, v30
	global_load_dwordx4 v[10:13], v[10:11], off
	s_nop 0
	global_load_dwordx4 v[14:17], v[14:15], off
	v_addc_co_u32_e32 v21, vcc, 0, v31, vcc
	v_add_co_u32_e32 v22, vcc, s16, v30
	global_load_dwordx2 v[38:39], v[36:37], off offset:-4096
	s_nop 0
	v_addc_co_u32_e32 v23, vcc, 0, v31, vcc
	v_add_co_u32_e32 v26, vcc, s17, v30
	global_load_dwordx4 v[18:21], v[20:21], off
	s_nop 0
	global_load_dwordx4 v[22:25], v[22:23], off
	v_addc_co_u32_e32 v27, vcc, 0, v31, vcc
	v_add_co_u32_e32 v30, vcc, s18, v30
	global_load_dwordx4 v[26:29], v[26:27], off
	s_nop 0
	v_addc_co_u32_e32 v31, vcc, 0, v31, vcc
	global_load_dwordx4 v[30:33], v[30:31], off
	s_lshl_b32 s22, s21, 3
	s_ashr_i32 s23, s22, 31
	s_waitcnt vmcnt(30)
	v_add_co_u32_e32 v40, vcc, s19, v36
	s_lshl_b64 s[22:23], s[22:23], 18
	s_nop 0
	v_addc_co_u32_e32 v41, vcc, -1, v37, vcc
	v_lshl_add_u64 v[34:35], v[34:35], 0, s[22:23]
	s_waitcnt vmcnt(29)
	v_add_co_u32_e32 v44, vcc, s1, v34
	global_load_dwordx2 v[42:43], v[36:37], off
	s_nop 0
	v_addc_co_u32_e32 v45, vcc, 0, v35, vcc
	v_add_co_u32_e32 v46, vcc, s13, v34
	s_waitcnt vmcnt(8)
	v_pk_add_f32 v[4:5], v[4:5], v[8:9]
	v_pk_add_f32 v[2:3], v[2:3], v[6:7]
	v_addc_co_u32_e32 v47, vcc, 0, v35, vcc
	v_add_co_u32_e32 v48, vcc, s14, v34
	s_waitcnt vmcnt(7)
	v_pk_add_f32 v[4:5], v[4:5], v[12:13]
	v_pk_add_f32 v[2:3], v[2:3], v[10:11]
	s_waitcnt vmcnt(6)
	v_pk_add_f32 v[4:5], v[4:5], v[16:17]
	v_pk_add_f32 v[2:3], v[2:3], v[14:15]
	v_addc_co_u32_e32 v49, vcc, 0, v35, vcc
	s_waitcnt vmcnt(5)
	v_lshlrev_b32_e32 v50, 16, v38
	v_and_b32_e32 v51, 0xffff0000, v38
	v_lshlrev_b32_e32 v38, 16, v39
	v_and_b32_e32 v39, 0xffff0000, v39
	s_waitcnt vmcnt(4)
	v_pk_add_f32 v[4:5], v[4:5], v[20:21]
	v_pk_add_f32 v[2:3], v[2:3], v[18:19]
	s_waitcnt vmcnt(3)
	v_pk_add_f32 v[4:5], v[4:5], v[24:25]
	v_pk_add_f32 v[2:3], v[2:3], v[22:23]
	v_add_co_u32_e32 v18, vcc, s15, v34
	s_waitcnt vmcnt(2)
	v_pk_add_f32 v[4:5], v[4:5], v[28:29]
	v_pk_add_f32 v[2:3], v[2:3], v[26:27]
	v_addc_co_u32_e32 v19, vcc, 0, v35, vcc
	s_waitcnt vmcnt(1)
	v_pk_add_f32 v[4:5], v[4:5], v[32:33]
	v_pk_add_f32 v[2:3], v[2:3], v[30:31]
	v_pk_fma_f32 v[4:5], v[38:39], s[8:9], v[4:5] op_sel_hi:[1,0,1]
	v_pk_fma_f32 v[2:3], v[50:51], s[8:9], v[2:3] op_sel_hi:[1,0,1]
	v_add_co_u32_e32 v22, vcc, s16, v34
	v_cvt_pk_bf16_f32 v2, v2, v3
	v_cvt_pk_bf16_f32 v3, v4, v5
	global_store_dwordx2 v[40:41], v[2:3], off
	v_addc_co_u32_e32 v23, vcc, 0, v35, vcc
	global_load_dwordx4 v[2:5], v[34:35], off
	global_load_dwordx4 v[6:9], v[44:45], off
	global_load_dwordx4 v[10:13], v[46:47], off
	global_load_dwordx4 v[14:17], v[48:49], off
	v_add_co_u32_e32 v26, vcc, s17, v34
	global_load_dwordx4 v[18:21], v[18:19], off
	s_nop 0
	global_load_dwordx4 v[22:25], v[22:23], off
	v_addc_co_u32_e32 v27, vcc, 0, v35, vcc
	v_add_co_u32_e32 v30, vcc, s18, v34
	global_load_dwordx4 v[26:29], v[26:27], off
	s_nop 0
	v_addc_co_u32_e32 v31, vcc, 0, v35, vcc
	global_load_dwordx4 v[30:33], v[30:31], off
	s_waitcnt vmcnt(9)
	v_lshlrev_b32_e32 v38, 16, v42
	v_and_b32_e32 v39, 0xffff0000, v42
	v_lshlrev_b32_e32 v40, 16, v43
	v_and_b32_e32 v41, 0xffff0000, v43
	v_add_co_u32_e32 v34, vcc, 0xf7800000, v36
	s_waitcnt vmcnt(6)
	v_pk_add_f32 v[4:5], v[4:5], v[8:9]
	v_pk_add_f32 v[2:3], v[2:3], v[6:7]
	s_waitcnt vmcnt(5)
	v_pk_add_f32 v[4:5], v[4:5], v[12:13]
	v_pk_add_f32 v[2:3], v[2:3], v[10:11]
	s_waitcnt vmcnt(4)
	v_pk_add_f32 v[4:5], v[4:5], v[16:17]
	v_pk_add_f32 v[2:3], v[2:3], v[14:15]
	s_waitcnt vmcnt(3)
	v_pk_add_f32 v[4:5], v[4:5], v[20:21]
	v_pk_add_f32 v[2:3], v[2:3], v[18:19]
	s_waitcnt vmcnt(2)
	v_pk_add_f32 v[4:5], v[4:5], v[24:25]
	v_pk_add_f32 v[2:3], v[2:3], v[22:23]
	s_waitcnt vmcnt(1)
	v_pk_add_f32 v[4:5], v[4:5], v[28:29]
	v_pk_add_f32 v[2:3], v[2:3], v[26:27]
	v_addc_co_u32_e32 v35, vcc, -1, v37, vcc
	s_waitcnt vmcnt(0)
	v_pk_add_f32 v[4:5], v[4:5], v[32:33]
	v_pk_add_f32 v[2:3], v[2:3], v[30:31]
	v_pk_fma_f32 v[4:5], v[40:41], s[8:9], v[4:5] op_sel_hi:[1,0,1]
	v_pk_fma_f32 v[2:3], v[38:39], s[8:9], v[2:3] op_sel_hi:[1,0,1]
	s_nop 0
	v_cvt_pk_bf16_f32 v2, v2, v3
	v_cvt_pk_bf16_f32 v3, v4, v5
	global_store_dwordx2 v[34:35], v[2:3], off
	s_branch .LBB0_1471
